# P4 balance: workgroups 0-63 take 14 B/C units instead of 12 (the rest 17 each), since the faster A loop made their extra 16-row A unit cheaper
# baseline (speedup 1.0000x reference)
; #define LAS __attribute__((address_space(3)))
; __device__ __forceinline__ unsigned xb_ld(unsigned* p)              { return __hip_atomic_load(p, __ATOMIC_RELAXED, __HIP_MEMORY_SCOPE_AGENT); }
; __device__ __forceinline__ unsigned xb_add(unsigned* p, unsigned v) { return __hip_atomic_fetch_add(p, v, __ATOMIC_RELAXED, __HIP_MEMORY_SCOPE_AGENT); }
; __device__ __forceinline__ unsigned xb_xcc_id() { return (unsigned)__builtin_amdgcn_s_getreg((3 << 11) | 20) & 0xFu; }
; __device__ __forceinline__ XcdBarrier xcd_barrier_post(unsigned* bar, volatile LAS unsigned* st) {
;     XcdBarrier b; b.bar = bar; b.x = xb_xcc_id(); b.st = st;
;     if (threadIdx.x == 0) (void)xb_add(&bar[XB_XCNT(b.x)], 1u);
;     return b;
; }
; __device__ __forceinline__ void xcd_barrier_complete(unsigned* bar, unsigned x, unsigned& nloc, unsigned& nx) {
;     const unsigned G = gridDim.x * gridDim.y * gridDim.z;
;     unsigned sum, cnt, mine, sp = 0u;
;     for (;;) {
;         sum = 0u; cnt = 0u; mine = 0u;
; #pragma unroll
;         for (unsigned j = 0; j < 16; ++j) { const unsigned c = xb_ld(&bar[XB_XCNT(j)]); sum += c; cnt += (c > 0u) ? 1u : 0u; mine = (j == x) ? c : mine; }
; __global__ void __launch_bounds__(512, 2) fwd_kernel(Args a) {
;     ...
;     { volatile LAS unsigned* misc = (volatile LAS unsigned*)(lds + MISC_OFF); if (threadIdx.x < 2) misc[threadIdx.x] = 0u; __syncthreads(); }
;     XcdBarrier xbar = xcd_barrier_post((unsigned*)(a.ws + OFF_BAR), (volatile LAS unsigned*)(lds + MISC_OFF));
;     ...
;     const int G = gridDim.x, ngw = G * 8;
;     float* SS = (float*)(a.ws + OFF_SS); bf16_t* HB = (bf16_t*)(a.ws + OFF_HB); bf16_t* WB = (bf16_t*)(a.ws + OFF_W);
;     bf16_t* Y = (bf16_t*)(a.ws + OFF_Y); bf16_t* MG = (bf16_t*)(a.ws + OFF_MG); bf16_t* R = (bf16_t*)(a.ws + OFF_R);
.LBB0_14:
	s_add_u32 s0, s54, 0xa00000
	s_addc_u32 s1, s55, 0
	v_writelane_b32 v252, s0, 21
	v_mov_b32_e32 v236, 0x358637bd
	v_mov_b64_e32 v[194:195], 0x1600
	v_writelane_b32 v252, s1, 22
	s_add_u32 s0, s54, 0x8b00000
	s_addc_u32 s1, s55, 0
	s_add_u32 s10, s54, 0xbf00000
	s_addc_u32 s11, s55, 0
	s_add_u32 s68, s54, 0x18000000
	s_addc_u32 s69, s55, 0
	s_add_u32 s70, s54, 0x20100000
	v_writelane_b32 v252, s0, 23
	s_addc_u32 s71, s55, 0
	v_mov_b64_e32 v[196:197], 0x15ff
	v_writelane_b32 v252, s1, 24
	s_add_u32 s0, s54, 0xff40000
	s_addc_u32 s1, s55, 0
	v_writelane_b32 v252, s0, 25
	v_mov_b64_e32 v[198:199], 0x400
	v_mov_b64_e32 v[200:201], 0x3ff
	v_writelane_b32 v252, s1, 26
	s_add_u32 s0, s54, 0x13f80000
	s_addc_u32 s1, s55, 0
	v_writelane_b32 v252, s0, 27
	s_add_u32 s4, s54, 0xac00000
	s_addc_u32 s5, s55, 0
	v_writelane_b32 v252, s1, 28
	v_writelane_b32 v252, s4, 29
	s_mul_i32 s0, s37, s36
	s_mul_i32 s0, s0, s26
	v_writelane_b32 v252, s5, 30
	s_add_u32 s4, s54, 0xa900000
	s_addc_u32 s5, s55, 0
	v_writelane_b32 v252, s4, 31
	v_mbcnt_hi_u32_b32 v237, -1, v6
	v_mov_b32_e32 v240, 0x80
	v_writelane_b32 v252, s5, 32
	s_add_u32 s4, s54, 0xa300000
	s_addc_u32 s5, s55, 0
	v_writelane_b32 v252, s4, 33
	v_mov_b32_e32 v241, 0x60
	v_mov_b32_e32 v242, 0xf149f2ca
	v_writelane_b32 v252, s5, 34
	s_add_u32 s4, s54, 0x9b80000
	s_addc_u32 s5, s55, 0
	s_cmp_lg_u64 s[80:81], 0
	v_writelane_b32 v252, s4, 35
	s_cselect_b64 s[24:25], -1, 0
	s_cmp_eq_u32 s36, 0
	v_writelane_b32 v252, s5, 36
	s_cselect_b64 s[4:5], -1, 0
	s_add_u32 s88, s54, 0x880200
	s_addc_u32 s89, s55, 0
	s_add_u32 s84, s54, 0x880400
	s_addc_u32 s85, s55, 0
	s_add_u32 s92, s54, 0x880500
	s_addc_u32 s93, s55, 0
	v_writelane_b32 v252, s4, 37
	s_add_u32 s90, s54, 0x880600
	s_addc_u32 s91, s55, 0
	v_writelane_b32 v252, s5, 38
	v_writelane_b32 v252, s0, 39
	s_add_u32 s0, s54, 0x880700
	s_addc_u32 s1, s55, 0
	v_writelane_b32 v252, s0, 40
	v_mov_b64_e32 v[204:205], 0xbff
	s_movk_i32 s97, 0x1600
	v_writelane_b32 v252, s1, 41
	s_add_u32 s0, s54, 0x880800
	s_addc_u32 s1, s55, 0
	v_writelane_b32 v252, s0, 42
	s_movk_i32 s37, 0x1010
	s_movk_i32 s86, 0x84
	v_writelane_b32 v252, s1, 43
	s_add_u32 s0, s54, 0x880900
	s_addc_u32 s1, s55, 0
	v_writelane_b32 v252, s0, 44
	s_movk_i32 s87, 0xff80
	s_mov_b64 s[20:21], 0x100
	v_writelane_b32 v252, s1, 45
	s_add_u32 s0, s54, 0x880a00
	s_addc_u32 s1, s55, 0
	v_writelane_b32 v252, s0, 46
	s_nop 1
	v_writelane_b32 v252, s1, 47
	s_add_u32 s0, s54, 0x880b00
	s_addc_u32 s1, s55, 0
	v_writelane_b32 v252, s0, 48
	s_nop 1
	v_writelane_b32 v252, s1, 49
	s_add_u32 s0, s54, 0x880c00
	s_addc_u32 s1, s55, 0
	v_writelane_b32 v252, s0, 50
	s_nop 1
	v_writelane_b32 v252, s1, 51
	s_add_u32 s0, s54, 0x880d00
	s_addc_u32 s1, s55, 0
	v_writelane_b32 v252, s0, 52
	s_nop 1
	v_writelane_b32 v252, s1, 53
	s_add_u32 s0, s54, 0x880e00
	s_addc_u32 s1, s55, 0
	v_writelane_b32 v252, s0, 54
	s_nop 1
	v_writelane_b32 v252, s1, 55
	s_add_u32 s0, s54, 0x880f00
	s_addc_u32 s1, s55, 0
	v_writelane_b32 v252, s0, 56
	s_nop 1
	v_writelane_b32 v252, s1, 57
	s_add_u32 s0, s54, 0x881000
	s_addc_u32 s1, s55, 0
	v_writelane_b32 v252, s0, 58
	s_nop 1
	v_writelane_b32 v252, s1, 59
	s_add_u32 s0, s54, 0x881100
	s_addc_u32 s1, s55, 0
	v_writelane_b32 v252, s0, 60
	s_nop 1
	v_writelane_b32 v252, s1, 61
	s_add_u32 s0, s54, 0x881200
	s_addc_u32 s1, s55, 0
	v_writelane_b32 v252, s0, 62
	s_nop 1
	v_writelane_b32 v252, s1, 63
	s_add_u32 s0, s54, 0x881300
	s_addc_u32 s1, s55, 0
	v_writelane_b32 v253, s0, 0
	s_cmp_eq_u32 s3, 15
	v_readlane_b32 s13, v252, 20
	v_writelane_b32 v253, s1, 1
	s_cselect_b64 s[0:1], -1, 0
	v_writelane_b32 v253, s0, 2
	s_cmp_eq_u32 s3, 14
	s_nop 0
	v_writelane_b32 v253, s1, 3
	s_cselect_b64 s[0:1], -1, 0
	v_writelane_b32 v253, s0, 4
	s_cmp_eq_u32 s3, 13
	s_nop 0
	v_writelane_b32 v253, s1, 5
	s_cselect_b64 s[0:1], -1, 0
	v_writelane_b32 v253, s0, 6
	s_cmp_eq_u32 s3, 12
	s_nop 0
	v_writelane_b32 v253, s1, 7
	s_cselect_b64 s[0:1], -1, 0
	v_writelane_b32 v253, s0, 8
	s_cmp_eq_u32 s3, 11
	s_nop 0
	v_writelane_b32 v253, s1, 9
	s_cselect_b64 s[0:1], -1, 0
	v_writelane_b32 v253, s0, 10
	s_cmp_eq_u32 s3, 10
	s_nop 0
	v_writelane_b32 v253, s1, 11
	s_cselect_b64 s[0:1], -1, 0
	v_writelane_b32 v253, s0, 12
	s_cmp_eq_u32 s3, 9
	s_nop 0
	v_writelane_b32 v253, s1, 13
	s_cselect_b64 s[0:1], -1, 0
	v_writelane_b32 v253, s0, 14
	s_cmp_eq_u32 s3, 8
	s_nop 0
	v_writelane_b32 v253, s1, 15
	s_cselect_b64 s[0:1], -1, 0
	v_writelane_b32 v253, s0, 16
	s_cmp_eq_u32 s3, 7
	s_nop 0
	v_writelane_b32 v253, s1, 17
	s_cselect_b64 s[0:1], -1, 0
	v_writelane_b32 v253, s0, 18
	s_cmp_eq_u32 s3, 6
	s_nop 0
	v_writelane_b32 v253, s1, 19
	s_cselect_b64 s[0:1], -1, 0
	v_writelane_b32 v253, s0, 20
	s_cmp_eq_u32 s3, 5
	s_nop 0
	v_writelane_b32 v253, s1, 21
	s_cselect_b64 s[0:1], -1, 0
	v_writelane_b32 v253, s0, 22
	s_cmp_eq_u32 s3, 4
	s_nop 0
	v_writelane_b32 v253, s1, 23
	s_cselect_b64 s[0:1], -1, 0
	v_writelane_b32 v253, s0, 24
	s_cmp_eq_u32 s3, 3
	s_nop 0
	v_writelane_b32 v253, s1, 25
	s_cselect_b64 s[0:1], -1, 0
	v_writelane_b32 v253, s0, 26
	s_cmp_eq_u32 s3, 2
	s_nop 0
	v_writelane_b32 v253, s1, 27
	s_cselect_b64 s[0:1], -1, 0
	v_writelane_b32 v253, s0, 28
	s_cmp_eq_u32 s3, 1
	s_nop 0
	v_writelane_b32 v253, s1, 29
	s_cselect_b64 s[0:1], -1, 0
	v_writelane_b32 v253, s0, 30
	s_cmp_eq_u32 s3, 0
	s_nop 0
	v_writelane_b32 v253, s1, 31
	s_cselect_b64 s[0:1], -1, 0
	v_writelane_b32 v253, s0, 32
	s_nop 1
	v_writelane_b32 v253, s1, 33
	s_lshl_b32 s0, s3, 8
	s_add_u32 s0, s28, s0
	s_addc_u32 s1, s29, 0
	s_add_u32 s4, s0, 0x1400
	s_addc_u32 s5, s1, 0
	v_writelane_b32 v253, s4, 34
	s_add_u32 s0, s0, 0x2400
	s_addc_u32 s1, s1, 0
	v_writelane_b32 v253, s5, 35
; #define RUN_BC(j) do { const int u_ = (j) >> 1, k_ = u_ / (NBATCH * 65); if ((j) & 1) { attn_unit<2>(P, u_, (LAS char*)lds, k_ != keyC); keyC = k_; } else { attn_unit<1>(P, u_, (LAS char*)lds, k_ != keyB); keyB = k_; } } while (0)
;     __device__ bool next(int i, Unit& u) const {
;         const long L = (long)i * G + c; if (L >= nwg) return false;
;         int wgid = (int)L; { const int q = nwg / NXCD, r = nwg % NXCD, xcd = wgid % NXCD, off = wgid / NXCD; wgid = (xcd < r ? xcd * (q + 1) : r * (q + 1) + (xcd - r) * q) + off; }
;         const int nig = WGM * nN, gid = wgid / nig, fm = gid * WGM, gsz = (nM - fm) < WGM ? (nM - fm) : WGM;
;         u.pm = fm + ((wgid % nig) % gsz); u.pn = (wgid % nig) / gsz; return true;
; __global__ void __launch_bounds__(512, 2) fwd_kernel(Args a) {
;     ...
;           constexpr int NBC = NUB + NUC, N1 = 12, NLOW = 64 * N1;
;           const int wg = blockIdx.x;
;           int keyB = -1, keyC = -1;
;     ...
;           if (G == 256) {
;               if (wg < 64) { for (int j = (wg & 7) * 8 + (wg >> 3); j < NLOW; j += 64) RUN_BC(j); }
;               else { for (int j = NLOW + (wg & 7) * 24 + ((wg - 64) >> 3); j < NBC; j += 192) RUN_BC(j); }
	v_writelane_b32 v253, s0, 36
	s_nop 1
	v_writelane_b32 v253, s1, 37
	s_add_u32 s0, s54, 0x883400
	s_addc_u32 s1, s55, 0
	v_writelane_b32 v253, s0, 38
	s_nop 1
	v_writelane_b32 v253, s1, 39
	s_add_u32 s0, s54, 0x883500
	s_addc_u32 s1, s55, 0
	v_writelane_b32 v253, s0, 40
	s_cmpk_lt_i32 s2, 0x1600
	s_nop 0
	v_writelane_b32 v253, s1, 41
	s_cselect_b64 s[0:1], -1, 0
	v_writelane_b32 v253, s0, 42
	s_ashr_i32 s33, s2, 31
	s_ashr_i32 s95, s36, 31
	v_writelane_b32 v253, s1, 43
	s_lshr_b32 s0, s33, 29
	s_add_i32 s0, s2, s0
	s_ashr_i32 s3, s0, 3
	s_and_b32 s0, s0, -8
	s_sub_i32 s4, s2, s0
	s_add_u32 s0, s54, 0x9600000
	s_addc_u32 s1, s55, 0
	v_writelane_b32 v253, s0, 44
	s_cmpk_lt_i32 s2, 0x400
	s_nop 0
	v_writelane_b32 v253, s1, 45
	s_cselect_b64 s[0:1], -1, 0
	s_lshl_b32 s5, s4, 7
	v_writelane_b32 v253, s0, 46
	s_cmpk_lt_u32 s2, 0x80
	s_nop 0
	v_writelane_b32 v253, s1, 47
	s_cselect_b64 s[0:1], -1, 0
	v_writelane_b32 v253, s0, 48
	s_nop 1
	v_writelane_b32 v253, s1, 49
	s_lshl_b32 s0, s2, 1
	s_and_b32 s6, s0, 0xe0
	s_and_b32 s0, s2, 15
	v_writelane_b32 v253, s0, 50
	s_lshl_b32 s0, s0, 6
	s_cmpk_lt_i32 s2, 0xf00
	v_writelane_b32 v253, s0, 51
	s_cselect_b64 s[0:1], -1, 0
	v_writelane_b32 v253, s0, 52
	s_cmpk_lg_i32 s36, 0x100
	s_nop 0
	v_writelane_b32 v253, s1, 53
	s_cselect_b64 s[0:1], -1, 0
	v_writelane_b32 v253, s0, 54
	s_cmpk_lt_i32 s2, 0x840
	s_cselect_b64 s[8:9], -1, 0
	v_writelane_b32 v253, s1, 55
	s_mul_i32 s0, s2, 33
	s_add_i32 s0, s0, 32
	s_mul_hi_u32 s7, s0, 0x3e0f83e1
	v_writelane_b32 v253, s8, 56
	s_lshr_b32 s1, s7, 3
	s_and_b32 s14, s2, 3
	v_writelane_b32 v253, s9, 57
	s_mul_i32 s8, s1, 33
	s_sub_i32 s8, s0, s8
	s_lshr_b32 s0, s7, 5
	s_lshl_b32 s7, s8, 7
	v_writelane_b32 v253, s7, 58
	s_lshr_b32 s7, s2, 3
	s_and_b32 s12, s2, 7
	v_writelane_b32 v253, s7, 59
	s_lshl_b32 s7, s14, 8
	s_add_u32 s8, s70, s7
	v_writelane_b32 v253, s14, 60
	s_addc_u32 s9, s71, 0
	v_writelane_b32 v253, s8, 61
	s_mulk_i32 s1, 0x1080
	s_mov_b32 s96, s14
	v_writelane_b32 v253, s9, 62
	s_mul_i32 s8, s0, 0x1e1e000
	s_add_u32 s8, s70, s8
	s_addc_u32 s9, s71, 0
	s_add_u32 s8, s8, s7
	s_addc_u32 s9, s9, 0
	v_writelane_b32 v253, s8, 63
	s_mulk_i32 s0, 0x1010
	s_nop 0
	v_writelane_b32 v254, s9, 0
	s_add_u32 s8, s10, s7
	v_writelane_b32 v254, s10, 1
	s_addc_u32 s9, s11, 0
	s_cmpk_lt_i32 s2, 0x1040
	v_writelane_b32 v254, s11, 2
	v_writelane_b32 v254, s8, 3
	s_nop 1
	v_writelane_b32 v254, s9, 4
	s_cselect_b64 s[8:9], -1, 0
	v_writelane_b32 v254, s8, 5
	s_cmp_gt_i32 s2, 63
	s_nop 0
	v_writelane_b32 v254, s9, 6
	v_sub_co_u32_e64 v1, s[8:9], s2, 64
	s_nop 0
	v_readfirstlane_b32 s7, v1
	v_writelane_b32 v254, s8, 7
	v_lshrrev_b32_e32 v1, 20, v0
	v_lshrrev_b32_e32 v0, 10, v0
	v_writelane_b32 v254, s9, 8
	s_cselect_b64 s[8:9], -1, 0
	v_writelane_b32 v254, s8, 9
	s_lshr_b32 s7, s7, 3
	v_or_b32_e32 v0, v0, v1
	v_writelane_b32 v254, s9, 10
	s_mul_i32 s8, s12, 24
	s_add_i32 s7, s7, s8
	s_addk_i32 s7, 0x380
	v_writelane_b32 v254, s12, 11
	s_cmpk_lt_u32 s7, 0x1040
	v_writelane_b32 v254, s7, 12
	s_cselect_b64 s[8:9], -1, 0
	v_writelane_b32 v254, s8, 13
	s_and_b32 s7, s13, 56
	v_mov_b32_e32 v1, 0
	v_writelane_b32 v254, s9, 14
	s_ashr_i32 s8, s2, 3
	s_add_i32 s7, s7, s8
	s_cmpk_lt_i32 s7, 0x380
	v_writelane_b32 v254, s7, 15
	s_cselect_b64 s[8:9], -1, 0
	v_writelane_b32 v254, s8, 16
	s_cmpk_lt_i32 s2, 0xc00
	s_nop 0
	v_writelane_b32 v254, s9, 17
	s_cselect_b64 s[8:9], -1, 0
	s_lshl_b32 s7, s2, 6
	v_writelane_b32 v254, s8, 18
	s_and_b32 s7, s7, 0x3c0
	s_nop 0
	v_writelane_b32 v254, s9, 19
	s_add_u32 s8, s54, 0xae00000
	v_writelane_b32 v254, s7, 20
	s_addc_u32 s9, s55, 0
	v_writelane_b32 v254, s8, 21
	s_mul_i32 s7, s4, 0x81
	s_nop 0
	v_writelane_b32 v254, s9, 22
	s_add_u32 s8, s54, 0xb900000
	s_addc_u32 s9, s55, 0
	s_cmp_lt_i32 s4, 0
	s_cselect_b32 s5, s7, s5
	s_movk_i32 s7, 0x2c1
	v_writelane_b32 v254, s8, 23
	s_cselect_b32 s7, s7, 0x2c0
	s_mul_i32 s7, s4, s7
	v_writelane_b32 v254, s9, 24
	s_movk_i32 s8, 0x1e1
	s_movk_i32 s9, 0x181
	s_cselect_b32 s8, s8, 0x1e0
	s_cselect_b32 s9, s9, 0x180
	s_add_i32 s7, s7, s3
	s_mul_hi_i32 s10, s7, 0x2e8ba2e9
	s_lshr_b32 s11, s10, 31
	s_ashr_i32 s10, s10, 5
	s_add_i32 s10, s10, s11
	s_mul_i32 s11, s10, 0xb0
	s_sub_i32 s7, s7, s11
	s_bfe_u32 s11, s7, 0x3001c
	s_add_i32 s11, s7, s11
	s_and_b32 s12, s11, 0xfff8
	s_sub_i32 s7, s7, s12
	s_lshl_b32 s10, s10, 3
	s_sext_i32_i16 s7, s7
	s_add_i32 s5, s5, s3
	s_add_i32 s15, s10, s7
	s_ashr_i32 s7, s5, 31
	s_lshr_b32 s7, s7, 27
	s_add_i32 s7, s5, s7
	s_and_b32 s10, s7, 0xffe0
	s_sub_i32 s5, s5, s10
	s_bfe_i32 s10, s5, 0x80000
	s_bfe_u32 s10, s10, 0x3000c
	s_add_i32 s10, s5, s10
	s_and_b32 s12, s10, 0xf8
	s_sub_i32 s5, s5, s12
	s_ashr_i32 s7, s7, 5
	s_lshl_b32 s7, s7, 3
	s_sext_i32_i8 s5, s5
	s_add_i32 s16, s7, s5
	s_mul_i32 s5, s4, s8
	s_add_i32 s5, s5, s3
	s_mul_hi_i32 s7, s5, 0x88888889
	s_add_i32 s7, s7, s5
	s_lshr_b32 s8, s7, 31
	s_ashr_i32 s7, s7, 6
	s_add_i32 s7, s7, s8
	s_mul_i32 s8, s7, 0x78
	s_sub_i32 s5, s5, s8
	s_bfe_i32 s8, s5, 0x80000
; #define LAS __attribute__((address_space(3)))
; __device__ __forceinline__ unsigned cvtpk(float lo, float hi) { f32x2_t v = {lo, hi}; bf16x2_t b = __builtin_convertvector(v, bf16x2_t); return __builtin_bit_cast(unsigned, b); }
; #define GSYNC0() do { asm volatile("s_waitcnt vmcnt(0) lgkmcnt(0)" ::: "memory"); __builtin_amdgcn_fence(__ATOMIC_RELEASE, "agent"); grid.sync(); __builtin_amdgcn_fence(__ATOMIC_ACQUIRE, "agent"); } while (0)
; __global__ void __launch_bounds__(512, 2) fwd_kernel(Args a) {
;     ...
;     { volatile LAS unsigned* misc = (volatile LAS unsigned*)(lds + MISC_OFF); if (threadIdx.x < 2) misc[threadIdx.x] = 0u; __syncthreads(); }
;     XcdBarrier xbar = xcd_barrier_post((unsigned*)(a.ws + OFF_BAR), (volatile LAS unsigned*)(lds + MISC_OFF));
;     ...
;     const int G = gridDim.x, ngw = G * 8;
;     float* SS = (float*)(a.ws + OFF_SS); bf16_t* HB = (bf16_t*)(a.ws + OFF_HB); bf16_t* WB = (bf16_t*)(a.ws + OFF_W);
;     bf16_t* Y = (bf16_t*)(a.ws + OFF_Y); bf16_t* MG = (bf16_t*)(a.ws + OFF_MG); bf16_t* R = (bf16_t*)(a.ws + OFF_R);
;     bf16_t* YA = Y; bf16_t* YB = Y + (size_t)MROWS * 512; bf16_t* YC = Y + (size_t)2 * MROWS * 512;
;     { int tid1 = threadIdx.x; asm volatile("" : "+v"(tid1)); const int lane = tid1 & 63, gw = blockIdx.x * 8 + __builtin_amdgcn_readfirstlane(tid1 >> 6);
;     for (int row = gw; row < MROWS; row += ngw) {
;         const int b = row / LT, t = row - b * LT;
;         const float* src = t < NMETA ? a.meta + (size_t)t * DM : a.x + ((size_t)b * SEQ + (t - NMETA)) * DM;
;         bf16_t* hb = HB + (size_t)row * DM; float q = 0.f;
; #pragma unroll
;         for (int j = 0; j < 4; ++j) { const f32x4 v = *(const f32x4*)(src + j * 256 + lane * 4);
;             q += (v[0] * v[0] + v[1] * v[1]) + (v[2] * v[2] + v[3] * v[3]); u32x2 wv; wv.x = cvtpk(v[0], v[1]); wv.y = cvtpk(v[2], v[3]); *(u32x2*)(hb + j * 256 + lane * 4) = wv; }
; #pragma unroll
;         for (int s = 1; s < 64; s <<= 1) q += __shfl_xor(q, s);
;         if (lane < 16) SS[(size_t)row * 16 + lane] = lane == 0 ? q : 0.f;
;     } }
;     for (int l = 0; l < DEPTH; ++l) {
;         conv_layer(a, l, WB, lds, ngw);
;         if (gridDim.x == 0) GSYNC0();
;     ...
;         constexpr size_t SSB = (size_t)MROWS * 16; const float* ss0 = SS + ((3 * l) & 1) * SSB; float* ss1 = SS + ((3 * l + 1) & 1) * SSB; float* ss2 = SS + ((3 * l + 2) & 1) * SSB; float* ss3 = SS + ((3 * l + 3) & 1) * SSB;
	s_bfe_u32 s8, s8, 0x3000c
	s_add_i32 s8, s5, s8
	s_and_b32 s12, s8, 0xf8
	s_sub_i32 s5, s5, s12
	s_lshl_b32 s7, s7, 3
	s_sext_i32_i8 s5, s5
	s_add_i32 s12, s7, s5
	s_mul_i32 s5, s4, s9
	s_sext_i32_i16 s4, s11
	s_ashr_i32 s7, s4, 3
	s_lshr_b32 s4, s4, 3
	v_writelane_b32 v254, s7, 25
	s_bfe_i64 s[18:19], s[4:5], 0x100000
	v_writelane_b32 v254, s18, 26
	s_bfe_i32 s4, s10, 0x80000
	s_sext_i32_i16 s7, s4
	v_writelane_b32 v254, s19, 27
	s_or_b32 s4, s6, 0x10000
	v_writelane_b32 v254, s4, 28
	s_bfe_i32 s4, s8, 0x80000
	s_sext_i32_i16 s4, s4
	s_ashr_i32 s6, s4, 3
	s_lshr_b32 s4, s4, 3
	v_writelane_b32 v254, s6, 29
	s_bfe_i64 s[8:9], s[4:5], 0x100000
	v_writelane_b32 v254, s8, 30
	s_ashr_i32 s4, s15, 31
	s_ashr_i32 s6, s12, 31
	v_writelane_b32 v254, s9, 31
	v_writelane_b32 v254, s15, 32
	v_writelane_b32 v254, s4, 33
	s_ashr_i32 s4, s7, 3
	v_writelane_b32 v254, s4, 34
	s_lshr_b32 s4, s7, 3
	v_writelane_b32 v254, s12, 35
	s_bitcmp1_b32 s2, 3
	v_writelane_b32 v254, s6, 36
	s_cselect_b64 s[6:7], -1, 0
	s_add_i32 s5, s5, s3
	v_writelane_b32 v254, s6, 37
	s_mul_hi_i32 s3, s5, 0x2aaaaaab
	s_movk_i32 s9, 0xff00
	v_writelane_b32 v254, s7, 38
	s_lshr_b32 s6, s3, 31
	s_ashr_i32 s3, s3, 4
	s_add_i32 s3, s3, s6
	s_mul_i32 s6, s3, 0x60
	s_sub_i32 s5, s5, s6
	s_bfe_i32 s6, s5, 0x80000
	s_bfe_u32 s6, s6, 0x3000c
	s_add_i32 s6, s5, s6
	s_and_b32 s7, s6, 0xf8
	s_sub_i32 s5, s5, s7
	s_lshl_b32 s3, s3, 3
	s_sext_i32_i8 s5, s5
	s_add_i32 s5, s3, s5
	s_bfe_i32 s3, s6, 0x80000
	s_sext_i32_i16 s3, s3
	s_ashr_i32 s6, s3, 3
	v_writelane_b32 v254, s6, 39
	s_lshr_b32 s6, s3, 3
	s_bfe_i64 s[6:7], s[6:7], 0x100000
	v_writelane_b32 v254, s6, 40
	s_ashr_i32 s3, s5, 31
	s_mov_b32 s10, 0x41000000
	v_writelane_b32 v254, s7, 41
	v_writelane_b32 v254, s5, 42
	s_add_u32 s6, s54, 0xaa00000
	v_writelane_b32 v254, s3, 43
	s_addc_u32 s7, s55, 0
	v_writelane_b32 v254, s6, 44
	s_movk_i32 s11, 0xff0
	s_mov_b64 s[18:19], 0x80
	v_writelane_b32 v254, s7, 45
	s_add_u32 s6, s54, 0xab00000
	v_writelane_b32 v254, s40, 46
	s_addc_u32 s7, s55, 0
	s_bfe_i64 s[4:5], s[4:5], 0x100000
	v_writelane_b32 v255, s4, 0
	s_ashr_i32 s3, s16, 31
	v_writelane_b32 v254, s41, 47
	v_writelane_b32 v255, s5, 1
	v_writelane_b32 v255, s16, 2
	v_writelane_b32 v255, s3, 3
	s_add_i32 s3, s13, 0xffffe800
	v_writelane_b32 v255, s3, 4
	s_lshl_b32 s3, s2, 8
	v_writelane_b32 v255, s3, 5
	s_lshl_b32 s3, s36, 8
	v_writelane_b32 v255, s3, 6
	s_lshl_b32 s3, s2, 4
	v_writelane_b32 v255, s3, 7
	s_lshl_b32 s3, s36, 4
	s_add_u32 s4, s80, 56
	v_writelane_b32 v255, s3, 8
	s_addc_u32 s5, s81, 0
	v_writelane_b32 v255, s4, 9
	s_mul_i32 s3, s2, 0x1080
	s_sub_i32 s1, s1, s3
	v_writelane_b32 v255, s5, 10
	v_writelane_b32 v255, s1, 11
	v_writelane_b32 v255, s0, 12
	s_lshl_b32 s0, s2, 5
	v_writelane_b32 v255, s0, 13
	s_lshl_b32 s0, s36, 5
	v_writelane_b32 v255, s0, 14
	s_lshl_b32 s0, s2, 2
	v_writelane_b32 v255, s0, 15
	s_lshl_b32 s0, s36, 2
	v_writelane_b32 v255, s0, 16
	s_add_i32 s0, 0, 0x21000
	v_writelane_b32 v255, s0, 17
	s_add_i32 s0, 0, 0x21004
	v_writelane_b32 v255, s0, 18
	s_add_i32 s0, 0, 0x20000
	v_writelane_b32 v255, s0, 19
	s_add_i32 s0, 0, 0x1fc00
	v_writelane_b32 v255, s0, 20
	s_add_i32 s0, 0, 0x1b800
	v_writelane_b32 v255, s0, 21
	s_add_i32 s0, 0, 0x1b000
	v_writelane_b32 v255, s0, 22
	s_add_i32 s0, 0, 0x1c010
	v_writelane_b32 v255, s0, 23
	s_add_i32 s0, 0, 0x1c40c
	s_movk_i32 s1, 0x3ff
	v_writelane_b32 v255, s0, 24
	s_add_i32 s0, 0, 0x184a0
	v_and_or_b32 v0, v0, s1, v234
	v_writelane_b32 v255, s0, 25
	s_mov_b64 s[0:1], 0
	v_writelane_b32 v255, s0, 26
	v_writelane_b32 v254, s42, 48
	v_writelane_b32 v254, s43, 49
	v_writelane_b32 v255, s1, 27
	v_cmp_eq_u32_e64 s[0:1], 0, v0
	v_writelane_b32 v254, s44, 50
	v_writelane_b32 v254, s45, 51
	v_writelane_b32 v255, s0, 28
	v_writelane_b32 v254, s46, 52
	v_writelane_b32 v254, s47, 53
	v_writelane_b32 v255, s1, 29
	s_mov_b64 s[0:1], 56
	v_writelane_b32 v255, s0, 30
	v_writelane_b32 v254, s48, 54
	v_writelane_b32 v254, s49, 55
	v_writelane_b32 v255, s1, 31
	s_mov_b64 s[0:1], 0
	v_writelane_b32 v255, s0, 32
	v_writelane_b32 v254, s50, 56
	v_writelane_b32 v254, s51, 57
	v_writelane_b32 v255, s1, 33
	s_mov_b32 s0, s94
	v_writelane_b32 v255, s0, 34
	v_writelane_b32 v254, s52, 58
	v_writelane_b32 v254, s53, 59
	v_writelane_b32 v255, s1, 35
	v_writelane_b32 v255, s88, 36
	v_writelane_b32 v254, s54, 60
	v_writelane_b32 v254, s55, 61
	v_writelane_b32 v255, s89, 37
	v_writelane_b32 v255, s84, 38
	v_writelane_b32 v254, s6, 62
	s_mov_b32 s81, 0
	v_writelane_b32 v255, s85, 39
	v_writelane_b32 v255, s92, 40
	v_writelane_b32 v254, s7, 63
	s_movk_i32 s3, 0x80
	v_writelane_b32 v255, s93, 41
	v_writelane_b32 v255, s95, 42
	v_writelane_b32 v255, s90, 43
	s_mov_b32 s50, 0x800000
	s_movk_i32 s51, 0x1e00
	v_writelane_b32 v255, s91, 44
	s_movk_i32 s6, 0x101
	s_movk_i32 s7, 0x5a
	s_add_i32 s8, 0, 0x1f800
	s_add_i32 s17, 0, 0x1a510
	s_movk_i32 s5, 0x1800
	s_mov_b32 s4, 0x3a800000
	s_mov_b32 s64, s81
	v_writelane_b32 v255, s96, 45
	s_branch .LBB0_17

; #define RUN_BC(j) do { const int u_ = (j) >> 1, k_ = u_ / (NBATCH * 65); if ((j) & 1) { attn_unit<2>(P, u_, (LAS char*)lds, k_ != keyC); keyC = k_; } else { attn_unit<1>(P, u_, (LAS char*)lds, k_ != keyB); keyB = k_; } } while (0)
; __global__ void __launch_bounds__(512, 2) fwd_kernel(Args a) {
;     ...
;               if (wg < 64) { for (int j = (wg & 7) * 8 + (wg >> 3); j < NLOW; j += 64) RUN_BC(j); }
.LBB0_1191:
	s_add_i32 s0, s27, 64
	s_xor_b32 s0, s0, 1
	s_cmpk_gt_i32 s27, 0x33f
	s_mov_b32 s27, s0
	s_cbranch_scc1 .LBB0_1373
